# P0a adaLN GEMV partials: next batch of 16 row loads issued before the FMAs of the current batch
# speedup vs baseline: 1.0061x; 1.0061x over previous
; __device__ __forceinline__ void p0_mod_item(Frame& F, const Params& p, int item) {
;     ...
;     const int ks = item / 6, cb = item % 6, k0 = ks * KS;
;     __syncthreads();
;     for (int i = F.tid; i < 3 * KS; i += NTHREADS) { const int r = i / KS, k = i % KS; const float c = (r < 2) ? p.in[1][r * D + k0 + k] : p.in[3][k0 + k]; sv[i] = c / (1.f + __expf(-c)); }
;     __syncthreads();
;     const int col = cb * 2048 + F.tid * 4;
;     const float* W = p.in[4] + (size_t)k0 * 12288 + col;
;     f32x4 a0 = {0, 0, 0, 0}, a1 = a0, a2 = a0;
; #pragma unroll 16
;     for (int k = 0; k < KS; ++k) { const f32x4 w = *(const f32x4*)(W + (size_t)k * 12288); a0 += w * sv[k]; a1 += w * sv[KS + k]; a2 += w * sv[2 * KS + k]; }
.LBB0_126:
	s_or_b64 exec, exec, s[4:5]
	s_mul_i32 s4, s8, 6
	s_sub_i32 s4, s2, s4
	s_lshl_b32 s6, s4, 11
	s_load_dwordx2 s[4:5], s[0:1], 0x20
	s_mul_hi_i32 s7, s9, 0xc000
	s_mul_i32 s9, s9, 0xc000
	v_lshl_add_u32 v14, v61, 2, s6
	v_ashrrev_i32_e32 v15, 31, v14
	s_waitcnt lgkmcnt(0)
	s_add_u32 s4, s4, s9
	s_addc_u32 s5, s5, s7
	v_mov_b32_e32 v2, 0
	s_mov_b32 s6, 0xc000
	v_lshl_add_u64 v[16:17], v[14:15], 2, s[4:5]
	s_mov_b64 s[98:99], s[4:5]
	v_lshlrev_b32_e32 v224, 2, v14
	s_mov_b64 s[4:5], 0
	s_mov_b32 s7, 0
	s_mov_b32 s9, 0x18000
	s_mov_b32 s10, 0x24000
	s_mov_b32 s11, 0x30000
	s_mov_b32 s12, 0x3c000
	s_mov_b32 s13, 0x48000
	s_mov_b32 s14, 0x54000
	s_mov_b32 s15, 0x60000
	s_mov_b32 s16, 0x6c000
	s_mov_b32 s17, 0x78000
	s_mov_b32 s18, 0x84000
	s_mov_b32 s19, 0x90000
	s_mov_b32 s20, 0x9c000
	s_mov_b32 s21, 0xa8000
	s_mov_b32 s22, 0xb4000
	v_mov_b32_e32 v3, v2
	v_mov_b32_e32 v4, v2
	v_mov_b32_e32 v5, v2
	v_mov_b32_e32 v6, v2
	v_mov_b32_e32 v7, v2
	v_mov_b32_e32 v8, v2
	v_mov_b32_e32 v9, v2
	v_mov_b32_e32 v10, v2
	v_mov_b32_e32 v11, v2
	v_mov_b32_e32 v12, v2
	v_mov_b32_e32 v13, v2
	s_barrier
	s_mov_b32 s100, 0
	s_add_u32 s100, s100, s98
	s_addc_u32 s101, s99, 0
	global_load_dwordx4 v[160:163], v224, s[100:101]
	s_add_u32 s100, s100, 0xc000
	s_addc_u32 s101, s101, 0
	global_load_dwordx4 v[164:167], v224, s[100:101]
	s_add_u32 s100, s100, 0xc000
	s_addc_u32 s101, s101, 0
	global_load_dwordx4 v[168:171], v224, s[100:101]
	s_add_u32 s100, s100, 0xc000
	s_addc_u32 s101, s101, 0
	global_load_dwordx4 v[172:175], v224, s[100:101]
	s_add_u32 s100, s100, 0xc000
	s_addc_u32 s101, s101, 0
	global_load_dwordx4 v[176:179], v224, s[100:101]
	s_add_u32 s100, s100, 0xc000
	s_addc_u32 s101, s101, 0
	global_load_dwordx4 v[180:183], v224, s[100:101]
	s_add_u32 s100, s100, 0xc000
	s_addc_u32 s101, s101, 0
	global_load_dwordx4 v[184:187], v224, s[100:101]
	s_add_u32 s100, s100, 0xc000
	s_addc_u32 s101, s101, 0
	global_load_dwordx4 v[188:191], v224, s[100:101]
	s_add_u32 s100, s100, 0xc000
	s_addc_u32 s101, s101, 0
	global_load_dwordx4 v[192:195], v224, s[100:101]
	s_add_u32 s100, s100, 0xc000
	s_addc_u32 s101, s101, 0
	global_load_dwordx4 v[196:199], v224, s[100:101]
	s_add_u32 s100, s100, 0xc000
	s_addc_u32 s101, s101, 0
	global_load_dwordx4 v[200:203], v224, s[100:101]
	s_add_u32 s100, s100, 0xc000
	s_addc_u32 s101, s101, 0
	global_load_dwordx4 v[204:207], v224, s[100:101]
	s_add_u32 s100, s100, 0xc000
	s_addc_u32 s101, s101, 0
	global_load_dwordx4 v[208:211], v224, s[100:101]
	s_add_u32 s100, s100, 0xc000
	s_addc_u32 s101, s101, 0
	global_load_dwordx4 v[212:215], v224, s[100:101]
	s_add_u32 s100, s100, 0xc000
	s_addc_u32 s101, s101, 0
	global_load_dwordx4 v[216:219], v224, s[100:101]
	s_add_u32 s100, s100, 0xc000
	s_addc_u32 s101, s101, 0
	global_load_dwordx4 v[220:223], v224, s[100:101]
.LBB0_127:
	s_waitcnt vmcnt(0)
	v_mov_b32_e32 v20, v160
	v_mov_b32_e32 v21, v161
	v_mov_b32_e32 v22, v162
	v_mov_b32_e32 v23, v163
	v_mov_b32_e32 v82, v164
	v_mov_b32_e32 v83, v165
	v_mov_b32_e32 v84, v166
	v_mov_b32_e32 v85, v167
	v_mov_b32_e32 v86, v168
	v_mov_b32_e32 v87, v169
	v_mov_b32_e32 v88, v170
	v_mov_b32_e32 v89, v171
	v_mov_b32_e32 v90, v172
	v_mov_b32_e32 v91, v173
	v_mov_b32_e32 v92, v174
	v_mov_b32_e32 v93, v175
	v_mov_b32_e32 v94, v176
	v_mov_b32_e32 v95, v177
	v_mov_b32_e32 v96, v178
	v_mov_b32_e32 v97, v179
	v_mov_b32_e32 v98, v180
	v_mov_b32_e32 v99, v181
	v_mov_b32_e32 v100, v182
	v_mov_b32_e32 v101, v183
	v_mov_b32_e32 v102, v184
	v_mov_b32_e32 v103, v185
	v_mov_b32_e32 v104, v186
	v_mov_b32_e32 v105, v187
	v_mov_b32_e32 v106, v188
	v_mov_b32_e32 v107, v189
	v_mov_b32_e32 v108, v190
	v_mov_b32_e32 v109, v191
	v_mov_b32_e32 v110, v192
	v_mov_b32_e32 v111, v193
	v_mov_b32_e32 v112, v194
	v_mov_b32_e32 v113, v195
	v_mov_b32_e32 v114, v196
	v_mov_b32_e32 v115, v197
	v_mov_b32_e32 v116, v198
	v_mov_b32_e32 v117, v199
	v_mov_b32_e32 v118, v200
	v_mov_b32_e32 v119, v201
	v_mov_b32_e32 v120, v202
	v_mov_b32_e32 v121, v203
	v_mov_b32_e32 v122, v204
	v_mov_b32_e32 v123, v205
	v_mov_b32_e32 v124, v206
	v_mov_b32_e32 v125, v207
	v_mov_b32_e32 v126, v208
	v_mov_b32_e32 v127, v209
	v_mov_b32_e32 v128, v210
	v_mov_b32_e32 v129, v211
	v_mov_b32_e32 v130, v212
	v_mov_b32_e32 v131, v213
	v_mov_b32_e32 v132, v214
	v_mov_b32_e32 v133, v215
	v_mov_b32_e32 v134, v216
	v_mov_b32_e32 v135, v217
	v_mov_b32_e32 v136, v218
	v_mov_b32_e32 v137, v219
	v_mov_b32_e32 v138, v220
	v_mov_b32_e32 v139, v221
	v_mov_b32_e32 v140, v222
	v_mov_b32_e32 v141, v223
	s_add_u32 s100, s4, 0xc0000
	s_cmp_lg_u32 s100, 0x600000
	s_cbranch_scc0 .Lmy_mod_nonext
	s_add_u32 s100, s100, s98
	s_addc_u32 s101, s99, 0
	global_load_dwordx4 v[160:163], v224, s[100:101]
	s_add_u32 s100, s100, 0xc000
	s_addc_u32 s101, s101, 0
	global_load_dwordx4 v[164:167], v224, s[100:101]
	s_add_u32 s100, s100, 0xc000
	s_addc_u32 s101, s101, 0
	global_load_dwordx4 v[168:171], v224, s[100:101]
	s_add_u32 s100, s100, 0xc000
	s_addc_u32 s101, s101, 0
	global_load_dwordx4 v[172:175], v224, s[100:101]
	s_add_u32 s100, s100, 0xc000
	s_addc_u32 s101, s101, 0
	global_load_dwordx4 v[176:179], v224, s[100:101]
	s_add_u32 s100, s100, 0xc000
	s_addc_u32 s101, s101, 0
	global_load_dwordx4 v[180:183], v224, s[100:101]
	s_add_u32 s100, s100, 0xc000
	s_addc_u32 s101, s101, 0
	global_load_dwordx4 v[184:187], v224, s[100:101]
	s_add_u32 s100, s100, 0xc000
	s_addc_u32 s101, s101, 0
	global_load_dwordx4 v[188:191], v224, s[100:101]
	s_add_u32 s100, s100, 0xc000
	s_addc_u32 s101, s101, 0
	global_load_dwordx4 v[192:195], v224, s[100:101]
	s_add_u32 s100, s100, 0xc000
	s_addc_u32 s101, s101, 0
	global_load_dwordx4 v[196:199], v224, s[100:101]
	s_add_u32 s100, s100, 0xc000
	s_addc_u32 s101, s101, 0
	global_load_dwordx4 v[200:203], v224, s[100:101]
	s_add_u32 s100, s100, 0xc000
	s_addc_u32 s101, s101, 0
	global_load_dwordx4 v[204:207], v224, s[100:101]
	s_add_u32 s100, s100, 0xc000
	s_addc_u32 s101, s101, 0
	global_load_dwordx4 v[208:211], v224, s[100:101]
	s_add_u32 s100, s100, 0xc000
	s_addc_u32 s101, s101, 0
	global_load_dwordx4 v[212:215], v224, s[100:101]
	s_add_u32 s100, s100, 0xc000
	s_addc_u32 s101, s101, 0
	global_load_dwordx4 v[216:219], v224, s[100:101]
	s_add_u32 s100, s100, 0xc000
	s_addc_u32 s101, s101, 0
	global_load_dwordx4 v[220:223], v224, s[100:101]
; __device__ __forceinline__ void p0_mod_item(Frame& F, const Params& p, int item) {
;     ...
; #pragma unroll 16
;     for (int k = 0; k < KS; ++k) { const f32x4 w = *(const f32x4*)(W + (size_t)k * 12288); a0 += w * sv[k]; a1 += w * sv[KS + k]; a2 += w * sv[2 * KS + k]; }
.Lmy_mod_nonext:
	s_nop 0
	v_mov_b32_e32 v1, s7
	s_nop 0
	ds_read_b128 v[24:27], v1
	ds_read_b128 v[28:31], v1 offset:16
	ds_read_b128 v[32:35], v1 offset:32
	ds_read_b128 v[36:39], v1 offset:48
	ds_read_b128 v[40:43], v1 offset:512
	ds_read_b128 v[48:51], v1 offset:528
	ds_read_b128 v[52:55], v1 offset:1024
	ds_read_b128 v[62:65], v1 offset:1040
	ds_read_b128 v[66:69], v1 offset:544
	ds_read_b128 v[70:73], v1 offset:560
	ds_read_b128 v[74:77], v1 offset:1056
	ds_read_b128 v[78:81], v1 offset:1072
	s_waitcnt lgkmcnt(10)
	v_mov_b32_e32 v58, v31
	s_waitcnt lgkmcnt(6)
	v_mov_b32_e32 v60, v51
	s_waitcnt lgkmcnt(4)
	v_mov_b32_e32 v142, v65
	v_mov_b32_e32 v144, v35
	s_nop 0
	s_waitcnt lgkmcnt(3)
	v_mov_b32_e32 v146, v69
	s_waitcnt lgkmcnt(1)
	v_mov_b32_e32 v148, v77
	s_add_u32 s4, s4, 0xc0000
	s_nop 0
	s_addc_u32 s5, s5, 0
	s_nop 0
	s_add_i32 s7, s7, 64
	s_nop 0
	v_mov_b32_e32 v150, v39
	s_nop 0
	s_nop 0
	s_nop 0
	s_nop 0
	s_nop 0
	s_nop 0
	s_nop 0
	v_mov_b32_e32 v18, v27
	v_mov_b32_e32 v44, v43
	v_mov_b32_e32 v56, v55
	v_mov_b32_e32 v152, v73
	s_waitcnt lgkmcnt(0)
	v_mov_b32_e32 v154, v81
	s_cmp_lg_u32 s4, 0x600000
	v_pk_fma_f32 v[4:5], v[22:23], v[24:25], v[4:5] op_sel_hi:[1,0,1]
	v_pk_fma_f32 v[2:3], v[20:21], v[24:25], v[2:3] op_sel_hi:[1,0,1]
	v_pk_fma_f32 v[12:13], v[22:23], v[40:41], v[12:13] op_sel_hi:[1,0,1]
	v_pk_fma_f32 v[10:11], v[20:21], v[40:41], v[10:11] op_sel_hi:[1,0,1]
	v_pk_fma_f32 v[8:9], v[22:23], v[52:53], v[8:9] op_sel_hi:[1,0,1]
	v_pk_fma_f32 v[6:7], v[20:21], v[52:53], v[6:7] op_sel_hi:[1,0,1]
	v_pk_fma_f32 v[2:3], v[82:83], v[24:25], v[2:3] op_sel:[0,1,0]
	v_pk_fma_f32 v[4:5], v[84:85], v[24:25], v[4:5] op_sel:[0,1,0]
	v_pk_fma_f32 v[10:11], v[82:83], v[40:41], v[10:11] op_sel:[0,1,0]
	v_pk_fma_f32 v[12:13], v[84:85], v[40:41], v[12:13] op_sel:[0,1,0]
	v_pk_fma_f32 v[6:7], v[82:83], v[52:53], v[6:7] op_sel:[0,1,0]
	v_pk_fma_f32 v[8:9], v[84:85], v[52:53], v[8:9] op_sel:[0,1,0]
	v_pk_fma_f32 v[4:5], v[88:89], v[26:27], v[4:5] op_sel_hi:[1,0,1]
	v_pk_fma_f32 v[2:3], v[86:87], v[26:27], v[2:3] op_sel_hi:[1,0,1]
	v_pk_fma_f32 v[12:13], v[88:89], v[42:43], v[12:13] op_sel_hi:[1,0,1]
	v_pk_fma_f32 v[10:11], v[86:87], v[42:43], v[10:11] op_sel_hi:[1,0,1]
	v_pk_fma_f32 v[8:9], v[88:89], v[54:55], v[8:9] op_sel_hi:[1,0,1]
	v_pk_fma_f32 v[6:7], v[86:87], v[54:55], v[6:7] op_sel_hi:[1,0,1]
	v_pk_fma_f32 v[4:5], v[92:93], v[18:19], v[4:5] op_sel_hi:[1,0,1]
	v_pk_fma_f32 v[2:3], v[90:91], v[18:19], v[2:3] op_sel_hi:[1,0,1]
	v_pk_fma_f32 v[12:13], v[92:93], v[44:45], v[12:13] op_sel_hi:[1,0,1]
	v_pk_fma_f32 v[10:11], v[90:91], v[44:45], v[10:11] op_sel_hi:[1,0,1]
	v_pk_fma_f32 v[8:9], v[92:93], v[56:57], v[8:9] op_sel_hi:[1,0,1]
	v_pk_fma_f32 v[6:7], v[90:91], v[56:57], v[6:7] op_sel_hi:[1,0,1]
	v_pk_fma_f32 v[4:5], v[96:97], v[28:29], v[4:5] op_sel_hi:[1,0,1]
	v_pk_fma_f32 v[2:3], v[94:95], v[28:29], v[2:3] op_sel_hi:[1,0,1]
	v_pk_fma_f32 v[12:13], v[96:97], v[48:49], v[12:13] op_sel_hi:[1,0,1]
	v_pk_fma_f32 v[10:11], v[94:95], v[48:49], v[10:11] op_sel_hi:[1,0,1]
	v_pk_fma_f32 v[8:9], v[96:97], v[62:63], v[8:9] op_sel_hi:[1,0,1]
	v_pk_fma_f32 v[6:7], v[94:95], v[62:63], v[6:7] op_sel_hi:[1,0,1]
	v_pk_fma_f32 v[4:5], v[100:101], v[28:29], v[4:5] op_sel:[0,1,0]
	v_pk_fma_f32 v[2:3], v[98:99], v[28:29], v[2:3] op_sel:[0,1,0]
	v_pk_fma_f32 v[12:13], v[100:101], v[48:49], v[12:13] op_sel:[0,1,0]
	v_pk_fma_f32 v[10:11], v[98:99], v[48:49], v[10:11] op_sel:[0,1,0]
	v_pk_fma_f32 v[8:9], v[100:101], v[62:63], v[8:9] op_sel:[0,1,0]
	v_pk_fma_f32 v[6:7], v[98:99], v[62:63], v[6:7] op_sel:[0,1,0]
	v_pk_fma_f32 v[4:5], v[104:105], v[30:31], v[4:5] op_sel_hi:[1,0,1]
	v_pk_fma_f32 v[2:3], v[102:103], v[30:31], v[2:3] op_sel_hi:[1,0,1]
	v_pk_fma_f32 v[12:13], v[104:105], v[50:51], v[12:13] op_sel_hi:[1,0,1]
	v_pk_fma_f32 v[10:11], v[102:103], v[50:51], v[10:11] op_sel_hi:[1,0,1]
	v_pk_fma_f32 v[8:9], v[104:105], v[64:65], v[8:9] op_sel_hi:[1,0,1]
	v_pk_fma_f32 v[6:7], v[102:103], v[64:65], v[6:7] op_sel_hi:[1,0,1]
	v_pk_fma_f32 v[4:5], v[108:109], v[58:59], v[4:5] op_sel_hi:[1,0,1]
	v_pk_fma_f32 v[2:3], v[106:107], v[58:59], v[2:3] op_sel_hi:[1,0,1]
	v_pk_fma_f32 v[12:13], v[108:109], v[60:61], v[12:13] op_sel_hi:[1,0,1]
; __device__ __forceinline__ void p0_mod_item(Frame& F, const Params& p, int item) {
;     ...
; #pragma unroll 16
;     for (int k = 0; k < KS; ++k) { const f32x4 w = *(const f32x4*)(W + (size_t)k * 12288); a0 += w * sv[k]; a1 += w * sv[KS + k]; a2 += w * sv[2 * KS + k]; }
;     float* o = (float*)(F.ws + WS_MODP) + (size_t)ks * 3 * 12288 + col;
;     *(f32x4*)o = a0; *(f32x4*)(o + 12288) = a1; *(f32x4*)(o + 2 * 12288) = a2;
	v_pk_fma_f32 v[10:11], v[106:107], v[60:61], v[10:11] op_sel_hi:[1,0,1]
	v_pk_fma_f32 v[8:9], v[108:109], v[142:143], v[8:9] op_sel_hi:[1,0,1]
	v_pk_fma_f32 v[6:7], v[106:107], v[142:143], v[6:7] op_sel_hi:[1,0,1]
	v_pk_fma_f32 v[4:5], v[112:113], v[32:33], v[4:5] op_sel_hi:[1,0,1]
	v_pk_fma_f32 v[2:3], v[110:111], v[32:33], v[2:3] op_sel_hi:[1,0,1]
	v_pk_fma_f32 v[12:13], v[112:113], v[66:67], v[12:13] op_sel_hi:[1,0,1]
	v_pk_fma_f32 v[10:11], v[110:111], v[66:67], v[10:11] op_sel_hi:[1,0,1]
	v_pk_fma_f32 v[8:9], v[112:113], v[74:75], v[8:9] op_sel_hi:[1,0,1]
	v_pk_fma_f32 v[6:7], v[110:111], v[74:75], v[6:7] op_sel_hi:[1,0,1]
	v_pk_fma_f32 v[4:5], v[116:117], v[32:33], v[4:5] op_sel:[0,1,0]
	v_pk_fma_f32 v[2:3], v[114:115], v[32:33], v[2:3] op_sel:[0,1,0]
	v_pk_fma_f32 v[12:13], v[116:117], v[66:67], v[12:13] op_sel:[0,1,0]
	v_pk_fma_f32 v[10:11], v[114:115], v[66:67], v[10:11] op_sel:[0,1,0]
	v_pk_fma_f32 v[8:9], v[116:117], v[74:75], v[8:9] op_sel:[0,1,0]
	v_pk_fma_f32 v[6:7], v[114:115], v[74:75], v[6:7] op_sel:[0,1,0]
	v_pk_fma_f32 v[4:5], v[120:121], v[34:35], v[4:5] op_sel_hi:[1,0,1]
	v_pk_fma_f32 v[2:3], v[118:119], v[34:35], v[2:3] op_sel_hi:[1,0,1]
	v_pk_fma_f32 v[12:13], v[120:121], v[68:69], v[12:13] op_sel_hi:[1,0,1]
	v_pk_fma_f32 v[10:11], v[118:119], v[68:69], v[10:11] op_sel_hi:[1,0,1]
	v_pk_fma_f32 v[8:9], v[120:121], v[76:77], v[8:9] op_sel_hi:[1,0,1]
	v_pk_fma_f32 v[6:7], v[118:119], v[76:77], v[6:7] op_sel_hi:[1,0,1]
	v_pk_fma_f32 v[4:5], v[124:125], v[144:145], v[4:5] op_sel_hi:[1,0,1]
	v_pk_fma_f32 v[2:3], v[122:123], v[144:145], v[2:3] op_sel_hi:[1,0,1]
	v_pk_fma_f32 v[12:13], v[124:125], v[146:147], v[12:13] op_sel_hi:[1,0,1]
	v_pk_fma_f32 v[10:11], v[122:123], v[146:147], v[10:11] op_sel_hi:[1,0,1]
	v_pk_fma_f32 v[8:9], v[124:125], v[148:149], v[8:9] op_sel_hi:[1,0,1]
	v_pk_fma_f32 v[6:7], v[122:123], v[148:149], v[6:7] op_sel_hi:[1,0,1]
	v_pk_fma_f32 v[4:5], v[128:129], v[36:37], v[4:5] op_sel_hi:[1,0,1]
	v_pk_fma_f32 v[2:3], v[126:127], v[36:37], v[2:3] op_sel_hi:[1,0,1]
	v_pk_fma_f32 v[12:13], v[128:129], v[70:71], v[12:13] op_sel_hi:[1,0,1]
	v_pk_fma_f32 v[10:11], v[126:127], v[70:71], v[10:11] op_sel_hi:[1,0,1]
	v_pk_fma_f32 v[8:9], v[128:129], v[78:79], v[8:9] op_sel_hi:[1,0,1]
	v_pk_fma_f32 v[6:7], v[126:127], v[78:79], v[6:7] op_sel_hi:[1,0,1]
	v_pk_fma_f32 v[4:5], v[132:133], v[36:37], v[4:5] op_sel:[0,1,0]
	v_pk_fma_f32 v[2:3], v[130:131], v[36:37], v[2:3] op_sel:[0,1,0]
	v_pk_fma_f32 v[12:13], v[132:133], v[70:71], v[12:13] op_sel:[0,1,0]
	v_pk_fma_f32 v[10:11], v[130:131], v[70:71], v[10:11] op_sel:[0,1,0]
	v_pk_fma_f32 v[8:9], v[132:133], v[78:79], v[8:9] op_sel:[0,1,0]
	v_pk_fma_f32 v[6:7], v[130:131], v[78:79], v[6:7] op_sel:[0,1,0]
	v_pk_fma_f32 v[4:5], v[136:137], v[38:39], v[4:5] op_sel_hi:[1,0,1]
	v_pk_fma_f32 v[2:3], v[134:135], v[38:39], v[2:3] op_sel_hi:[1,0,1]
	v_pk_fma_f32 v[12:13], v[136:137], v[72:73], v[12:13] op_sel_hi:[1,0,1]
	v_pk_fma_f32 v[10:11], v[134:135], v[72:73], v[10:11] op_sel_hi:[1,0,1]
	v_pk_fma_f32 v[8:9], v[136:137], v[80:81], v[8:9] op_sel_hi:[1,0,1]
	v_pk_fma_f32 v[6:7], v[134:135], v[80:81], v[6:7] op_sel_hi:[1,0,1]
	v_pk_fma_f32 v[4:5], v[140:141], v[150:151], v[4:5] op_sel_hi:[1,0,1]
	v_pk_fma_f32 v[2:3], v[138:139], v[150:151], v[2:3] op_sel_hi:[1,0,1]
	v_pk_fma_f32 v[12:13], v[140:141], v[152:153], v[12:13] op_sel_hi:[1,0,1]
	v_pk_fma_f32 v[10:11], v[138:139], v[152:153], v[10:11] op_sel_hi:[1,0,1]
	v_pk_fma_f32 v[8:9], v[140:141], v[154:155], v[8:9] op_sel_hi:[1,0,1]
	v_pk_fma_f32 v[6:7], v[138:139], v[154:155], v[6:7] op_sel_hi:[1,0,1]
	s_cbranch_scc1 .LBB0_127
	s_mul_i32 s4, s8, 3
	s_mul_i32 s8, s8, 0x24000
	s_mul_hi_i32 s5, s4, 0xc000
	s_add_u32 s4, s56, s8
	s_addc_u32 s5, s57, s5
	v_lshl_add_u64 v[14:15], v[14:15], 2, s[4:5]
	v_add_co_u32_e32 v16, vcc, 0x100000, v14
	s_nop 1
	v_addc_co_u32_e32 v17, vcc, 0, v15, vcc
	global_store_dwordx4 v[16:17], v[2:5], off
	s_nop 1
	v_add_co_u32_e32 v2, vcc, 0x10c000, v14
	s_nop 1
	v_addc_co_u32_e32 v3, vcc, 0, v15, vcc
	global_store_dwordx4 v[2:3], v[10:13], off
	v_add_co_u32_e32 v2, vcc, 0x118000, v14
	s_nop 1
	v_addc_co_u32_e32 v3, vcc, 0, v15, vcc
	global_store_dwordx4 v[2:3], v[6:9], off
